# adds scan_final counted waits, ss_phase 4 rows per iteration, kvpost K-part loads batched
# speedup vs baseline: 1.0059x; 1.0021x over previous
; __device__ __forceinline__ unsigned f2bf(float f) { unsigned u = __builtin_bit_cast(unsigned, f); return (u + 0x7fffu + ((u >> 16) & 1u)) >> 16; }
; __device__ __forceinline__ float bflo(unsigned w) { return __uint_as_float(w << 16); }
; __device__ __forceinline__ float bfhi(unsigned w) { return __uint_as_float(w & 0xffff0000u); }
; __device__ __forceinline__ void scan_final(const GAS unsigned* __restrict__ LU, const GAS f32x2* __restrict__ AGG, const GAS bf16_t* __restrict__ P, GAS bf16_t* __restrict__ A2, int gw, int NGW, int lane) {
;     ...
; #pragma unroll 1
;         for (int t0 = 0; t0 < CHL; t0 += BT) {
;             if (t0 + BT < CHL) {
; #pragma unroll
;                 for (int i = 0; i < BT; ++i) wn[i] = __builtin_nontemporal_load(LU + ((size_t)(row0 + t0 + BT + i) * 2 + 0) * 512 + ch); }
; #pragma unroll
;             for (int i = 0; i < BT; ++i) { hf = __builtin_amdgcn_exp2f(bflo(w[i])) * hf + bfhi(w[i]); A2[(size_t)(row0 + t0 + i) * DM + ch] = (bf16_t)f2bf(hf); }
; #pragma unroll
;             for (int i = 0; i < BT; ++i) w[i] = wn[i]; }
.LBB0_121:
	s_waitcnt vmcnt(0)
	s_add_i32 s12, s1, s24
	s_ashr_i32 s13, s12, 31
	s_lshl_b64 s[24:25], s[12:13], 11
	v_lshl_or_b32 v38, v46, 1, s24
	v_mov_b32_e32 v39, s25
	v_lshl_add_u64 v[42:43], s[6:7], 0, v[38:39]
	s_mov_b32 s1, 0
	s_cmpk_gt_u32 s1, 0xef
	s_cselect_b64 s[90:91], -1, 0
	s_and_b64 vcc, exec, s[90:91]
	s_cbranch_vccnz .LBB0_124
	s_branch .LBB0_123
.LBB0_122:
	s_waitcnt vmcnt(16)
	v_mov_b64_e32 v[32:33], v[16:17]
	v_mov_b64_e32 v[30:31], v[14:15]
	v_mov_b64_e32 v[28:29], v[12:13]
	v_mov_b64_e32 v[26:27], v[10:11]
	v_mov_b64_e32 v[24:25], v[8:9]
	v_mov_b64_e32 v[22:23], v[6:7]
	v_mov_b64_e32 v[20:21], v[4:5]
	v_mov_b64_e32 v[18:19], v[2:3]
	s_cmpk_gt_u32 s1, 0xef
	s_cselect_b64 s[90:91], -1, 0
	s_and_b64 vcc, exec, s[90:91]
	s_cbranch_vccnz .LBB0_124

; __device__ __forceinline__ unsigned f2bf(float f) { unsigned u = __builtin_bit_cast(unsigned, f); return (u + 0x7fffu + ((u >> 16) & 1u)) >> 16; }
; __device__ __forceinline__ float bflo(unsigned w) { return __uint_as_float(w << 16); }
; __device__ __forceinline__ float bfhi(unsigned w) { return __uint_as_float(w & 0xffff0000u); }
; __device__ __forceinline__ void scan_final(const GAS unsigned* __restrict__ LU, const GAS f32x2* __restrict__ AGG, const GAS bf16_t* __restrict__ P, GAS bf16_t* __restrict__ A2, int gw, int NGW, int lane) {
;     ...
;             for (int i = 0; i < BT; ++i) { hf = __builtin_amdgcn_exp2f(bflo(w[i])) * hf + bfhi(w[i]); A2[(size_t)(row0 + t0 + i) * DM + ch] = (bf16_t)f2bf(hf); }
.LBB0_124:
	v_lshlrev_b32_e32 v37, 16, v18
	v_exp_f32_e32 v37, v37
	v_and_b32_e32 v18, 0xffff0000, v18
	v_add_co_u32_e32 v44, vcc, 0xffff9000, v42
	v_fmac_f32_e32 v18, v45, v37
	v_bfe_u32 v37, v18, 16, 1
	v_lshlrev_b32_e32 v40, 16, v19
	v_add3_u32 v37, v18, v37, s61
	v_exp_f32_e32 v40, v40
	v_addc_co_u32_e32 v45, vcc, -1, v43, vcc
	global_store_short_d16_hi v[44:45], v37, off offset:-2048
	v_lshlrev_b32_e32 v37, 16, v20
	v_exp_f32_e32 v37, v37
	v_and_b32_e32 v19, 0xffff0000, v19
	v_fmac_f32_e32 v19, v40, v18
	v_bfe_u32 v18, v19, 16, 1
	v_and_b32_e32 v20, 0xffff0000, v20
	v_add3_u32 v18, v19, v18, s61
	v_fmac_f32_e32 v20, v37, v19
	global_store_short_d16_hi v[44:45], v18, off
	v_bfe_u32 v18, v20, 16, 1
	v_add3_u32 v37, v20, v18, s61
	v_lshlrev_b32_e32 v18, 16, v21
	v_exp_f32_e32 v40, v18
	v_add_co_u32_e32 v18, vcc, s15, v42
	v_and_b32_e32 v21, 0xffff0000, v21
	s_nop 0
	v_addc_co_u32_e32 v19, vcc, -1, v43, vcc
	v_fmac_f32_e32 v21, v40, v20
	global_store_short_d16_hi v[18:19], v37, off offset:-2048
	v_bfe_u32 v18, v21, 16, 1
	v_add3_u32 v20, v21, v18, s61
	v_lshlrev_b32_e32 v18, 16, v22
	v_exp_f32_e32 v37, v18
	s_movk_i32 s13, 0xb000
	v_add_co_u32_e32 v18, vcc, s13, v42
	s_movk_i32 s13, 0xc000
	s_nop 0
	v_addc_co_u32_e32 v19, vcc, -1, v43, vcc
	global_store_short_d16_hi v[18:19], v20, off offset:-4096
	v_and_b32_e32 v20, 0xffff0000, v22
	v_lshlrev_b32_e32 v22, 16, v23
	v_fmac_f32_e32 v20, v37, v21
	v_exp_f32_e32 v22, v22
	v_bfe_u32 v21, v20, 16, 1
	v_add3_u32 v21, v20, v21, s61
	global_store_short_d16_hi v[18:19], v21, off offset:-2048
	v_and_b32_e32 v21, 0xffff0000, v23
	v_fmac_f32_e32 v21, v22, v20
	v_lshlrev_b32_e32 v22, 16, v24
	v_exp_f32_e32 v22, v22
	v_bfe_u32 v20, v21, 16, 1
	v_add3_u32 v20, v21, v20, s61
	global_store_short_d16_hi v[18:19], v20, off
	v_and_b32_e32 v20, 0xffff0000, v24
	v_fmac_f32_e32 v20, v22, v21
	v_bfe_u32 v18, v20, 16, 1
	v_add3_u32 v21, v20, v18, s61
	v_lshlrev_b32_e32 v18, 16, v25
	v_exp_f32_e32 v22, v18
	v_add_co_u32_e32 v18, vcc, s13, v42
	s_movk_i32 s13, 0xd000
	s_nop 0
	v_addc_co_u32_e32 v19, vcc, -1, v43, vcc
	global_store_short_d16_hi v[18:19], v21, off offset:-2048
	v_and_b32_e32 v21, 0xffff0000, v25
	v_fmac_f32_e32 v21, v22, v20
	v_bfe_u32 v18, v21, 16, 1
	v_add3_u32 v20, v21, v18, s61
	v_lshlrev_b32_e32 v18, 16, v26
	v_exp_f32_e32 v22, v18
	v_add_co_u32_e32 v18, vcc, s13, v42
	s_movk_i32 s13, 0xe000
	s_nop 0
	v_addc_co_u32_e32 v19, vcc, -1, v43, vcc
	global_store_short_d16_hi v[18:19], v20, off offset:-4096
	v_and_b32_e32 v20, 0xffff0000, v26
	v_fmac_f32_e32 v20, v22, v21
	v_lshlrev_b32_e32 v22, 16, v27
	v_exp_f32_e32 v22, v22
	v_bfe_u32 v21, v20, 16, 1
	v_add3_u32 v21, v20, v21, s61
	global_store_short_d16_hi v[18:19], v21, off offset:-2048
	v_and_b32_e32 v21, 0xffff0000, v27
	v_fmac_f32_e32 v21, v22, v20
	v_lshlrev_b32_e32 v22, 16, v28
	v_exp_f32_e32 v22, v22
	v_bfe_u32 v20, v21, 16, 1
	v_add3_u32 v20, v21, v20, s61
	global_store_short_d16_hi v[18:19], v20, off
	v_and_b32_e32 v20, 0xffff0000, v28
	v_fmac_f32_e32 v20, v22, v21
	v_bfe_u32 v18, v20, 16, 1
	v_add3_u32 v21, v20, v18, s61
	v_lshlrev_b32_e32 v18, 16, v29
	v_exp_f32_e32 v22, v18
	v_add_co_u32_e32 v18, vcc, s13, v42
	s_movk_i32 s13, 0xf000
	s_nop 0
	v_addc_co_u32_e32 v19, vcc, -1, v43, vcc
	global_store_short_d16_hi v[18:19], v21, off offset:-2048
	v_and_b32_e32 v21, 0xffff0000, v29
	v_fmac_f32_e32 v21, v22, v20
	v_lshlrev_b32_e32 v22, 16, v30
	v_exp_f32_e32 v22, v22
	v_bfe_u32 v20, v21, 16, 1
	v_add3_u32 v20, v21, v20, s61
	global_store_short_d16_hi v[18:19], v20, off
	v_and_b32_e32 v20, 0xffff0000, v30
	v_fmac_f32_e32 v20, v22, v21
	v_bfe_u32 v18, v20, 16, 1
	v_add3_u32 v21, v20, v18, s61
	v_lshlrev_b32_e32 v18, 16, v31
	v_exp_f32_e32 v22, v18
	v_add_co_u32_e32 v18, vcc, s13, v42
	v_and_b32_e32 v45, 0xffff0000, v33
	s_nop 0
	v_addc_co_u32_e32 v19, vcc, -1, v43, vcc
	global_store_short_d16_hi v[18:19], v21, off offset:-2048
	v_and_b32_e32 v18, 0xffff0000, v31
	v_fmac_f32_e32 v18, v22, v20
	v_lshlrev_b32_e32 v20, 16, v32
	v_exp_f32_e32 v20, v20
	v_bfe_u32 v19, v18, 16, 1
	v_add3_u32 v19, v18, v19, s61
	global_store_short_d16_hi v[42:43], v19, off offset:-4096
	v_and_b32_e32 v19, 0xffff0000, v32
	v_fmac_f32_e32 v19, v20, v18
	v_lshlrev_b32_e32 v20, 16, v33
	v_exp_f32_e32 v20, v20
	v_bfe_u32 v18, v19, 16, 1
	v_add3_u32 v18, v19, v18, s61
	global_store_short_d16_hi v[42:43], v18, off offset:-2048
	v_fmac_f32_e32 v45, v20, v19
	v_bfe_u32 v18, v45, 16, 1
	v_add3_u32 v18, v45, v18, s61
	s_mov_b64 s[24:25], 0x8000
	s_add_i32 s1, s1, 16
	global_store_short_d16_hi v[42:43], v18, off
	v_lshl_add_u64 v[42:43], v[42:43], 0, s[24:25]
	s_and_b64 vcc, exec, s[90:91]
	s_cbranch_vccz .LBB0_122
; __device__ __forceinline__ void scan_final(const GAS unsigned* __restrict__ LU, const GAS f32x2* __restrict__ AGG, const GAS bf16_t* __restrict__ P, GAS bf16_t* __restrict__ A2, int gw, int NGW, int lane) {
;     ...
;         bf16_t gr[BT], grn[BT];
; #pragma unroll
;         for (int i = 0; i < BT; ++i) { w[i] = __builtin_nontemporal_load(LU + ((size_t)(row0 + CHL - BT + i) * 2 + 1) * 512 + ch); gr[i] = P[(size_t)(row0 + CHL - BT + i) * PW + 512 + ch]; }
	s_waitcnt vmcnt(0)
	s_or_b32 s24, s88, 0xf0
	s_ashr_i32 s25, s24, 31
	s_lshl_b64 s[26:27], s[24:25], 12
	s_add_u32 s26, s76, s26
	s_addc_u32 s27, s77, s27
	s_mul_i32 s13, s24, 0xc00
	s_mul_hi_i32 s1, s24, 0xc00
	s_add_u32 s24, s74, s13
	s_addc_u32 s25, s75, s1
	v_lshlrev_b32_e32 v42, 1, v1
	global_load_dword v18, v36, s[26:27] offset:2048 nt
	global_load_ushort v1, v42, s[24:25] offset:1024
	s_or_b32 s24, s88, 0xf1
	s_ashr_i32 s25, s24, 31
	s_lshl_b64 s[26:27], s[24:25], 12
	s_add_u32 s26, s76, s26
	s_addc_u32 s27, s77, s27
	s_mul_i32 s13, s24, 0xc00
	s_mul_hi_i32 s1, s24, 0xc00
	s_add_u32 s24, s74, s13
	s_addc_u32 s25, s75, s1
	global_load_dword v19, v36, s[26:27] offset:2048 nt
	global_load_ushort v40, v42, s[24:25] offset:1024
	s_or_b32 s24, s88, 0xf2
	s_ashr_i32 s25, s24, 31
	s_lshl_b64 s[26:27], s[24:25], 12
	s_add_u32 s26, s76, s26
	s_addc_u32 s27, s77, s27
	s_mul_i32 s13, s24, 0xc00
	s_mul_hi_i32 s1, s24, 0xc00
	s_add_u32 s24, s74, s13
	s_addc_u32 s25, s75, s1
	global_load_dword v20, v36, s[26:27] offset:2048 nt
	global_load_ushort v84, v42, s[24:25] offset:1024
	s_or_b32 s24, s88, 0xf3
	s_ashr_i32 s25, s24, 31
	s_lshl_b64 s[26:27], s[24:25], 12
	s_add_u32 s26, s76, s26
	s_addc_u32 s27, s77, s27
	s_mul_i32 s13, s24, 0xc00
	s_mul_hi_i32 s1, s24, 0xc00
	s_add_u32 s24, s74, s13
	s_addc_u32 s25, s75, s1
	global_load_dword v21, v36, s[26:27] offset:2048 nt
	global_load_ushort v85, v42, s[24:25] offset:1024
	s_or_b32 s24, s88, 0xf4
	s_ashr_i32 s25, s24, 31
	s_lshl_b64 s[26:27], s[24:25], 12
	s_add_u32 s26, s76, s26
	s_addc_u32 s27, s77, s27
	s_mul_i32 s13, s24, 0xc00
	s_mul_hi_i32 s1, s24, 0xc00
	s_add_u32 s24, s74, s13
	s_addc_u32 s25, s75, s1
	global_load_dword v22, v36, s[26:27] offset:2048 nt
	global_load_ushort v86, v42, s[24:25] offset:1024
	s_or_b32 s24, s88, 0xf5
	s_ashr_i32 s25, s24, 31
	s_lshl_b64 s[26:27], s[24:25], 12
	s_add_u32 s26, s76, s26
	s_addc_u32 s27, s77, s27
	s_mul_i32 s13, s24, 0xc00
	s_mul_hi_i32 s1, s24, 0xc00
	s_add_u32 s24, s74, s13
	s_addc_u32 s25, s75, s1
	global_load_dword v23, v36, s[26:27] offset:2048 nt
	global_load_ushort v87, v42, s[24:25] offset:1024
	s_or_b32 s24, s88, 0xf6
	s_ashr_i32 s25, s24, 31
	s_lshl_b64 s[26:27], s[24:25], 12
	s_add_u32 s26, s76, s26
	s_addc_u32 s27, s77, s27
	s_mul_i32 s13, s24, 0xc00
	s_mul_hi_i32 s1, s24, 0xc00
	s_add_u32 s24, s74, s13
	s_addc_u32 s25, s75, s1
	global_load_dword v24, v36, s[26:27] offset:2048 nt
	global_load_ushort v88, v42, s[24:25] offset:1024
	s_or_b32 s24, s88, 0xf7
	s_ashr_i32 s25, s24, 31
	s_lshl_b64 s[26:27], s[24:25], 12
	s_add_u32 s26, s76, s26
	s_addc_u32 s27, s77, s27
	s_mul_i32 s13, s24, 0xc00
	s_mul_hi_i32 s1, s24, 0xc00
	s_add_u32 s24, s74, s13
	s_addc_u32 s25, s75, s1
	global_load_dword v25, v36, s[26:27] offset:2048 nt
	global_load_ushort v91, v42, s[24:25] offset:1024
	s_or_b32 s24, s88, 0xf8
	s_ashr_i32 s25, s24, 31
	s_lshl_b64 s[26:27], s[24:25], 12
	s_add_u32 s26, s76, s26
	s_addc_u32 s27, s77, s27
	s_mul_i32 s13, s24, 0xc00
	s_mul_hi_i32 s1, s24, 0xc00
	s_add_u32 s24, s74, s13
	s_addc_u32 s25, s75, s1
	global_load_dword v26, v36, s[26:27] offset:2048 nt
	global_load_ushort v93, v42, s[24:25] offset:1024
	s_or_b32 s24, s88, 0xf9
	s_ashr_i32 s25, s24, 31
	s_lshl_b64 s[26:27], s[24:25], 12
	s_add_u32 s26, s76, s26
	s_addc_u32 s27, s77, s27
	s_mul_i32 s13, s24, 0xc00
	s_mul_hi_i32 s1, s24, 0xc00
	s_add_u32 s24, s74, s13
	s_addc_u32 s25, s75, s1
	global_load_dword v27, v36, s[26:27] offset:2048 nt
	global_load_ushort v95, v42, s[24:25] offset:1024
	s_or_b32 s24, s88, 0xfa
	s_ashr_i32 s25, s24, 31
	s_lshl_b64 s[26:27], s[24:25], 12
	s_add_u32 s26, s76, s26
	s_addc_u32 s27, s77, s27
	s_mul_i32 s13, s24, 0xc00
	s_mul_hi_i32 s1, s24, 0xc00
	s_add_u32 s24, s74, s13
	s_addc_u32 s25, s75, s1
	global_load_dword v28, v36, s[26:27] offset:2048 nt
	global_load_ushort v98, v42, s[24:25] offset:1024
	s_or_b32 s24, s88, 0xfb
	s_ashr_i32 s25, s24, 31
	s_lshl_b64 s[26:27], s[24:25], 12
	s_add_u32 s26, s76, s26
	s_addc_u32 s27, s77, s27
	s_mul_i32 s13, s24, 0xc00
	s_mul_hi_i32 s1, s24, 0xc00
	s_add_u32 s24, s74, s13
	s_addc_u32 s25, s75, s1
	global_load_dword v29, v36, s[26:27] offset:2048 nt
	global_load_ushort v100, v42, s[24:25] offset:1024
	s_or_b32 s24, s88, 0xfc
	s_ashr_i32 s25, s24, 31
	s_lshl_b64 s[26:27], s[24:25], 12
	s_add_u32 s26, s76, s26
	s_addc_u32 s27, s77, s27
	s_mul_i32 s13, s24, 0xc00
	s_mul_hi_i32 s1, s24, 0xc00
	s_add_u32 s24, s74, s13
	s_addc_u32 s25, s75, s1
	global_load_dword v30, v36, s[26:27] offset:2048 nt
	global_load_ushort v102, v42, s[24:25] offset:1024
	s_or_b32 s24, s88, 0xfd
	s_ashr_i32 s25, s24, 31
	s_lshl_b64 s[26:27], s[24:25], 12
	s_add_u32 s26, s76, s26
	s_addc_u32 s27, s77, s27
	s_mul_i32 s13, s24, 0xc00
	s_mul_hi_i32 s1, s24, 0xc00
	s_add_u32 s24, s74, s13
	s_addc_u32 s25, s75, s1
	global_load_dword v31, v36, s[26:27] offset:2048 nt
	global_load_ushort v104, v42, s[24:25] offset:1024
	s_or_b32 s24, s88, 0xfe
	s_ashr_i32 s25, s24, 31
	s_lshl_b64 s[26:27], s[24:25], 12
	s_add_u32 s26, s76, s26
	s_addc_u32 s27, s77, s27
	s_mul_i32 s13, s24, 0xc00
	s_mul_hi_i32 s1, s24, 0xc00
	s_add_u32 s24, s74, s13
	s_addc_u32 s25, s75, s1
	global_load_dword v32, v36, s[26:27] offset:2048 nt
	global_load_ushort v106, v42, s[24:25] offset:1024
	s_or_b32 s24, s88, 0xff
	s_ashr_i32 s25, s24, 31
	s_lshl_b64 s[26:27], s[24:25], 12
	s_add_u32 s26, s76, s26
	s_addc_u32 s27, s77, s27
	s_mul_i32 s13, s24, 0xc00
	s_mul_hi_i32 s1, s24, 0xc00
	s_add_u32 s24, s74, s13
	s_addc_u32 s25, s75, s1
	global_load_dword v33, v36, s[26:27] offset:2048 nt
	global_load_ushort v109, v42, s[24:25] offset:1024
	v_mov_b32_e32 v43, v0
	v_lshl_add_u64 v[36:37], s[74:75], 0, v[42:43]
	v_lshl_add_u64 v[38:39], s[8:9], 0, v[38:39]
	s_mov_b32 s1, 0

; __device__ __forceinline__ unsigned f2bf(float f) { unsigned u = __builtin_bit_cast(unsigned, f); return (u + 0x7fffu + ((u >> 16) & 1u)) >> 16; }
; __device__ __forceinline__ float bflo(unsigned w) { return __uint_as_float(w << 16); }
; __device__ __forceinline__ float bfhi(unsigned w) { return __uint_as_float(w & 0xffff0000u); }
; __device__ __forceinline__ float bf2f(bf16_t v) { return __uint_as_float((unsigned)v << 16); }
; __device__ __forceinline__ void scan_final(const GAS unsigned* __restrict__ LU, const GAS f32x2* __restrict__ AGG, const GAS bf16_t* __restrict__ P, GAS bf16_t* __restrict__ A2, int gw, int NGW, int lane) {
;     ...
;         for (int t0 = CHL - BT; t0 >= 0; t0 -= BT) { bf16_t f[BT];
; #pragma unroll
;             for (int i = 0; i < BT; ++i) f[i] = A2[(size_t)(row0 + t0 + i) * DM + ch];
;             if (t0 >= BT) {
; #pragma unroll
;                 for (int i = 0; i < BT; ++i) { wn[i] = __builtin_nontemporal_load(LU + ((size_t)(row0 + t0 - BT + i) * 2 + 1) * 512 + ch); grn[i] = P[(size_t)(row0 + t0 - BT + i) * PW + 512 + ch]; } }
; #pragma unroll
;             for (int i = BT - 1; i >= 0; --i) { hb = __builtin_amdgcn_exp2f(bflo(w[i])) * hb + bfhi(w[i]);
;                 A2[(size_t)(row0 + t0 + i) * DM + ch] = (bf16_t)f2bf((bf2f(f[i]) + hb) * gelu_tanh(bf2f(gr[i]))); }
.LBB0_128:
	s_waitcnt vmcnt(32)
.Lsf_b_go:
	v_lshlrev_b32_e32 v114, 16, v33
	v_exp_f32_e32 v114, v114
	v_and_b32_e32 v33, 0xffff0000, v33
	v_lshlrev_b32_e32 v109, 16, v109
	s_movk_i32 s24, 0x8800
	v_fmac_f32_e32 v33, v41, v114
	v_lshlrev_b32_e32 v41, 16, v113
	v_mul_f32_e32 v113, 0x3d372713, v109
	v_mul_f32_e32 v113, v113, v109
	v_fma_f32 v113, v113, v109, v109
	v_mul_f32_e32 v113, 0x3f4c422a, v113
	v_mul_f32_e32 v113, 0xc038aa3b, v113
	v_exp_f32_e32 v113, v113
	v_add_f32_e32 v41, v33, v41
	s_mov_b32 s25, -1
	v_lshl_add_u64 v[42:43], v[38:39], 0, s[24:25]
	v_add_f32_e32 v113, 1.0, v113
	v_rcp_f32_e32 v113, v113
	s_movk_i32 s24, 0x9000
	s_mov_b32 s25, -1
	v_lshl_add_u64 v[44:45], v[38:39], 0, s[24:25]
	v_mul_f32_e32 v109, v113, v109
	v_mul_f32_e32 v41, v109, v41
	v_bfe_u32 v109, v41, 16, 1
	v_add3_u32 v41, v41, v109, s61
	global_store_short_d16_hi v[38:39], v41, off
	v_lshlrev_b32_e32 v41, 16, v32
	v_exp_f32_e32 v41, v41
	v_and_b32_e32 v32, 0xffff0000, v32
	s_movk_i32 s24, 0x9800
	s_mov_b32 s25, -1
	v_fmac_f32_e32 v32, v41, v33
	v_lshlrev_b32_e32 v41, 16, v106
	v_mul_f32_e32 v106, 0x3d372713, v41
	v_mul_f32_e32 v106, v106, v41
	v_fma_f32 v106, v106, v41, v41
	v_mul_f32_e32 v106, 0x3f4c422a, v106
	v_mul_f32_e32 v106, 0xc038aa3b, v106
	v_exp_f32_e32 v106, v106
	v_lshlrev_b32_e32 v33, 16, v112
	v_add_f32_e32 v33, v32, v33
	v_lshl_add_u64 v[46:47], v[38:39], 0, s[24:25]
	v_add_f32_e32 v106, 1.0, v106
	v_rcp_f32_e32 v106, v106
	s_movk_i32 s24, 0xa000
	s_mov_b32 s25, -1
	v_lshl_add_u64 v[48:49], v[38:39], 0, s[24:25]
	v_mul_f32_e32 v41, v106, v41
	v_mul_f32_e32 v33, v41, v33
	v_bfe_u32 v41, v33, 16, 1
	v_add3_u32 v33, v33, v41, s61
	global_store_short_d16_hi v[38:39], v33, off offset:-2048
	v_lshlrev_b32_e32 v33, 16, v31
	v_exp_f32_e32 v33, v33
	v_and_b32_e32 v31, 0xffff0000, v31
	s_movk_i32 s24, 0xa800
	s_mov_b32 s25, -1
	v_fmac_f32_e32 v31, v33, v32
	v_lshlrev_b32_e32 v33, 16, v104
	v_mul_f32_e32 v41, 0x3d372713, v33
	v_mul_f32_e32 v41, v41, v33
	v_fma_f32 v41, v41, v33, v33
	v_mul_f32_e32 v41, 0x3f4c422a, v41
	v_mul_f32_e32 v41, 0xc038aa3b, v41
	v_exp_f32_e32 v41, v41
	v_lshlrev_b32_e32 v32, 16, v111
	v_add_f32_e32 v32, v31, v32
	v_lshl_add_u64 v[50:51], v[38:39], 0, s[24:25]
	v_add_f32_e32 v41, 1.0, v41
	v_rcp_f32_e32 v41, v41
	s_movk_i32 s24, 0xb000
	s_mov_b32 s25, -1
	v_lshl_add_u64 v[52:53], v[38:39], 0, s[24:25]
	v_mul_f32_e32 v33, v41, v33
	v_mul_f32_e32 v32, v33, v32
	v_bfe_u32 v33, v32, 16, 1
	v_add3_u32 v32, v32, v33, s61
	global_store_short_d16_hi v[38:39], v32, off offset:-4096
	v_lshlrev_b32_e32 v32, 16, v30
	v_exp_f32_e32 v32, v32
	v_and_b32_e32 v30, 0xffff0000, v30
	s_movk_i32 s24, 0xb800
	s_mov_b32 s25, -1
	v_fmac_f32_e32 v30, v32, v31
	v_lshlrev_b32_e32 v32, 16, v102
	v_mul_f32_e32 v33, 0x3d372713, v32
	v_mul_f32_e32 v33, v33, v32
	v_fma_f32 v33, v33, v32, v32
	v_mul_f32_e32 v33, 0x3f4c422a, v33
	v_mul_f32_e32 v33, 0xc038aa3b, v33
	v_lshl_add_u64 v[54:55], v[38:39], 0, s[24:25]
	s_movk_i32 s24, 0xc000
	v_exp_f32_e32 v33, v33
	s_mov_b32 s25, -1
	v_lshl_add_u64 v[56:57], v[38:39], 0, s[24:25]
	s_movk_i32 s24, 0xc800
	s_mov_b32 s25, -1
	v_lshl_add_u64 v[58:59], v[38:39], 0, s[24:25]
	s_movk_i32 s24, 0xd000
	v_add_f32_e32 v33, 1.0, v33
	s_mov_b32 s25, -1
	v_rcp_f32_e32 v33, v33
	v_lshl_add_u64 v[60:61], v[38:39], 0, s[24:25]
	s_movk_i32 s24, 0xd800
	s_mov_b32 s25, -1
	v_lshl_add_u64 v[62:63], v[38:39], 0, s[24:25]
	s_movk_i32 s24, 0xe000
	v_lshlrev_b32_e32 v31, 16, v110
	s_mov_b32 s25, -1
	v_add_f32_e32 v31, v30, v31
	v_mul_f32_e32 v32, v33, v32
	v_lshl_add_u64 v[64:65], v[38:39], 0, s[24:25]
	s_movk_i32 s24, 0xe800
	v_mul_f32_e32 v31, v32, v31
	s_mov_b32 s25, -1
	v_bfe_u32 v32, v31, 16, 1
	v_lshl_add_u64 v[66:67], v[38:39], 0, s[24:25]
	v_add3_u32 v31, v31, v32, s61
	global_store_short_d16_hi v[66:67], v31, off
	v_lshlrev_b32_e32 v31, 16, v29
	v_exp_f32_e32 v31, v31
	v_and_b32_e32 v29, 0xffff0000, v29
	v_and_b32_e32 v41, 0xffff0000, v18
	v_lshlrev_b32_e32 v1, 16, v1
	v_fmac_f32_e32 v29, v31, v30
	v_lshlrev_b32_e32 v31, 16, v100
	v_mul_f32_e32 v32, 0x3d372713, v31
	v_mul_f32_e32 v32, v32, v31
	v_fma_f32 v32, v32, v31, v31
	v_mul_f32_e32 v32, 0x3f4c422a, v32
	v_mul_f32_e32 v32, 0xc038aa3b, v32
	v_exp_f32_e32 v32, v32
	v_lshlrev_b32_e32 v30, 16, v108
	v_add_f32_e32 v30, v29, v30
	s_movk_i32 s24, 0x8000
	v_add_f32_e32 v32, 1.0, v32
	v_rcp_f32_e32 v32, v32
	s_add_i32 s1, s1, -16
	s_mov_b32 s25, -1
	v_lshl_add_u64 v[38:39], v[38:39], 0, s[24:25]
	v_mul_f32_e32 v31, v32, v31
	v_mul_f32_e32 v30, v31, v30
	v_bfe_u32 v31, v30, 16, 1
	v_add3_u32 v30, v30, v31, s61
	global_store_short_d16_hi v[64:65], v30, off
	v_lshlrev_b32_e32 v30, 16, v28
	v_exp_f32_e32 v30, v30
	v_and_b32_e32 v28, 0xffff0000, v28
	s_cmpk_eq_i32 s1, 0xff00
	v_fmac_f32_e32 v28, v30, v29
	v_lshlrev_b32_e32 v30, 16, v98
	v_mul_f32_e32 v31, 0x3d372713, v30
	v_mul_f32_e32 v31, v31, v30
	v_fma_f32 v31, v31, v30, v30
	v_mul_f32_e32 v31, 0x3f4c422a, v31
	v_mul_f32_e32 v31, 0xc038aa3b, v31
	v_exp_f32_e32 v31, v31
	v_lshlrev_b32_e32 v29, 16, v107
	v_add_f32_e32 v29, v28, v29
	v_add_f32_e32 v31, 1.0, v31
	v_rcp_f32_e32 v31, v31
	s_nop 0
	v_mul_f32_e32 v30, v31, v30
	v_mul_f32_e32 v29, v30, v29
	v_bfe_u32 v30, v29, 16, 1
	v_add3_u32 v29, v29, v30, s61
	global_store_short_d16_hi v[62:63], v29, off
	v_lshlrev_b32_e32 v29, 16, v27
	v_exp_f32_e32 v29, v29
	v_and_b32_e32 v27, 0xffff0000, v27
	v_fmac_f32_e32 v27, v29, v28
	v_lshlrev_b32_e32 v29, 16, v95
	v_mul_f32_e32 v30, 0x3d372713, v29
	v_mul_f32_e32 v30, v30, v29
	v_fma_f32 v30, v30, v29, v29
	v_mul_f32_e32 v30, 0x3f4c422a, v30
	v_mul_f32_e32 v30, 0xc038aa3b, v30
	v_exp_f32_e32 v30, v30
	v_lshlrev_b32_e32 v28, 16, v105
; __device__ __forceinline__ unsigned f2bf(float f) { unsigned u = __builtin_bit_cast(unsigned, f); return (u + 0x7fffu + ((u >> 16) & 1u)) >> 16; }
; __device__ __forceinline__ float bflo(unsigned w) { return __uint_as_float(w << 16); }
; __device__ __forceinline__ float bfhi(unsigned w) { return __uint_as_float(w & 0xffff0000u); }
; __device__ __forceinline__ float bf2f(bf16_t v) { return __uint_as_float((unsigned)v << 16); }
; __device__ __forceinline__ void scan_final(const GAS unsigned* __restrict__ LU, const GAS f32x2* __restrict__ AGG, const GAS bf16_t* __restrict__ P, GAS bf16_t* __restrict__ A2, int gw, int NGW, int lane) {
;     ...
;             for (int i = BT - 1; i >= 0; --i) { hb = __builtin_amdgcn_exp2f(bflo(w[i])) * hb + bfhi(w[i]);
;                 A2[(size_t)(row0 + t0 + i) * DM + ch] = (bf16_t)f2bf((bf2f(f[i]) + hb) * gelu_tanh(bf2f(gr[i]))); }
; #pragma unroll
;             for (int i = 0; i < BT; ++i) { w[i] = wn[i]; gr[i] = grn[i]; } }
	v_add_f32_e32 v28, v27, v28
	v_add_f32_e32 v30, 1.0, v30
	v_rcp_f32_e32 v30, v30
	s_nop 0
	v_mul_f32_e32 v29, v30, v29
	v_mul_f32_e32 v28, v29, v28
	v_bfe_u32 v29, v28, 16, 1
	v_add3_u32 v28, v28, v29, s61
	global_store_short_d16_hi v[60:61], v28, off
	v_lshlrev_b32_e32 v28, 16, v26
	v_exp_f32_e32 v28, v28
	v_and_b32_e32 v26, 0xffff0000, v26
	v_fmac_f32_e32 v26, v28, v27
	v_lshlrev_b32_e32 v28, 16, v93
	v_mul_f32_e32 v29, 0x3d372713, v28
	v_mul_f32_e32 v29, v29, v28
	v_fma_f32 v29, v29, v28, v28
	v_mul_f32_e32 v29, 0x3f4c422a, v29
	v_mul_f32_e32 v29, 0xc038aa3b, v29
	v_exp_f32_e32 v29, v29
	v_lshlrev_b32_e32 v27, 16, v103
	v_add_f32_e32 v27, v26, v27
	v_add_f32_e32 v29, 1.0, v29
	v_rcp_f32_e32 v29, v29
	s_nop 0
	v_mul_f32_e32 v28, v29, v28
	v_mul_f32_e32 v27, v28, v27
	v_bfe_u32 v28, v27, 16, 1
	v_add3_u32 v27, v27, v28, s61
	global_store_short_d16_hi v[58:59], v27, off
	v_lshlrev_b32_e32 v27, 16, v25
	v_exp_f32_e32 v27, v27
	v_and_b32_e32 v25, 0xffff0000, v25
	v_fmac_f32_e32 v25, v27, v26
	v_lshlrev_b32_e32 v27, 16, v91
	v_mul_f32_e32 v28, 0x3d372713, v27
	v_mul_f32_e32 v28, v28, v27
	v_fma_f32 v28, v28, v27, v27
	v_mul_f32_e32 v28, 0x3f4c422a, v28
	v_mul_f32_e32 v28, 0xc038aa3b, v28
	v_exp_f32_e32 v28, v28
	v_lshlrev_b32_e32 v26, 16, v101
	v_add_f32_e32 v26, v25, v26
	v_add_f32_e32 v28, 1.0, v28
	v_rcp_f32_e32 v28, v28
	s_nop 0
	v_mul_f32_e32 v27, v28, v27
	v_mul_f32_e32 v26, v27, v26
	v_bfe_u32 v27, v26, 16, 1
	v_add3_u32 v26, v26, v27, s61
	global_store_short_d16_hi v[56:57], v26, off
	v_lshlrev_b32_e32 v26, 16, v24
	v_exp_f32_e32 v26, v26
	v_and_b32_e32 v24, 0xffff0000, v24
	v_fmac_f32_e32 v24, v26, v25
	v_lshlrev_b32_e32 v26, 16, v88
	v_mul_f32_e32 v27, 0x3d372713, v26
	v_mul_f32_e32 v27, v27, v26
	v_fma_f32 v27, v27, v26, v26
	v_mul_f32_e32 v27, 0x3f4c422a, v27
	v_mul_f32_e32 v27, 0xc038aa3b, v27
	v_exp_f32_e32 v27, v27
	v_lshlrev_b32_e32 v25, 16, v99
	v_add_f32_e32 v25, v24, v25
	v_add_f32_e32 v27, 1.0, v27
	v_rcp_f32_e32 v27, v27
	s_nop 0
	v_mul_f32_e32 v26, v27, v26
	v_mul_f32_e32 v25, v26, v25
	v_bfe_u32 v26, v25, 16, 1
	v_add3_u32 v25, v25, v26, s61
	global_store_short_d16_hi v[54:55], v25, off
	v_lshlrev_b32_e32 v25, 16, v23
	v_exp_f32_e32 v25, v25
	v_and_b32_e32 v23, 0xffff0000, v23
	v_fmac_f32_e32 v23, v25, v24
	v_lshlrev_b32_e32 v25, 16, v87
	v_mul_f32_e32 v26, 0x3d372713, v25
	v_mul_f32_e32 v26, v26, v25
	v_fma_f32 v26, v26, v25, v25
	v_mul_f32_e32 v26, 0x3f4c422a, v26
	v_mul_f32_e32 v26, 0xc038aa3b, v26
	v_exp_f32_e32 v26, v26
	v_lshlrev_b32_e32 v24, 16, v97
	v_add_f32_e32 v24, v23, v24
	v_add_f32_e32 v26, 1.0, v26
	v_rcp_f32_e32 v26, v26
	s_nop 0
	v_mul_f32_e32 v25, v26, v25
	v_mul_f32_e32 v24, v25, v24
	v_bfe_u32 v25, v24, 16, 1
	v_add3_u32 v24, v24, v25, s61
	global_store_short_d16_hi v[52:53], v24, off
	v_lshlrev_b32_e32 v24, 16, v22
	v_exp_f32_e32 v24, v24
	v_and_b32_e32 v22, 0xffff0000, v22
	v_fmac_f32_e32 v22, v24, v23
	v_lshlrev_b32_e32 v24, 16, v86
	v_mul_f32_e32 v25, 0x3d372713, v24
	v_mul_f32_e32 v25, v25, v24
	v_fma_f32 v25, v25, v24, v24
	v_mul_f32_e32 v25, 0x3f4c422a, v25
	v_mul_f32_e32 v25, 0xc038aa3b, v25
	v_exp_f32_e32 v25, v25
	v_lshlrev_b32_e32 v23, 16, v96
	v_add_f32_e32 v23, v22, v23
	v_add_f32_e32 v25, 1.0, v25
	v_rcp_f32_e32 v25, v25
	s_nop 0
	v_mul_f32_e32 v24, v25, v24
	v_mul_f32_e32 v23, v24, v23
	v_bfe_u32 v24, v23, 16, 1
	v_add3_u32 v23, v23, v24, s61
	global_store_short_d16_hi v[50:51], v23, off
	v_lshlrev_b32_e32 v23, 16, v21
	v_exp_f32_e32 v23, v23
	v_and_b32_e32 v21, 0xffff0000, v21
	v_fmac_f32_e32 v21, v23, v22
	v_lshlrev_b32_e32 v23, 16, v85
	v_mul_f32_e32 v24, 0x3d372713, v23
	v_mul_f32_e32 v24, v24, v23
	v_fma_f32 v24, v24, v23, v23
	v_mul_f32_e32 v24, 0x3f4c422a, v24
	v_mul_f32_e32 v24, 0xc038aa3b, v24
	v_exp_f32_e32 v24, v24
	v_lshlrev_b32_e32 v22, 16, v94
	v_add_f32_e32 v22, v21, v22
	v_add_f32_e32 v24, 1.0, v24
	v_rcp_f32_e32 v24, v24
	s_nop 0
	v_mul_f32_e32 v23, v24, v23
	v_mul_f32_e32 v22, v23, v22
	v_bfe_u32 v23, v22, 16, 1
	v_add3_u32 v22, v22, v23, s61
	global_store_short_d16_hi v[48:49], v22, off
	v_lshlrev_b32_e32 v22, 16, v20
	v_exp_f32_e32 v22, v22
	v_and_b32_e32 v20, 0xffff0000, v20
	v_fmac_f32_e32 v20, v22, v21
	v_lshlrev_b32_e32 v22, 16, v84
	v_mul_f32_e32 v23, 0x3d372713, v22
	v_mul_f32_e32 v23, v23, v22
	v_fma_f32 v23, v23, v22, v22
	v_mul_f32_e32 v23, 0x3f4c422a, v23
	v_mul_f32_e32 v23, 0xc038aa3b, v23
	v_exp_f32_e32 v23, v23
	v_lshlrev_b32_e32 v21, 16, v92
	v_add_f32_e32 v21, v20, v21
	v_add_f32_e32 v23, 1.0, v23
	v_rcp_f32_e32 v23, v23
	s_nop 0
	v_mul_f32_e32 v22, v23, v22
	v_mul_f32_e32 v21, v22, v21
	v_bfe_u32 v22, v21, 16, 1
	v_add3_u32 v21, v21, v22, s61
	global_store_short_d16_hi v[46:47], v21, off
	v_lshlrev_b32_e32 v21, 16, v19
	v_exp_f32_e32 v21, v21
	v_and_b32_e32 v19, 0xffff0000, v19
	v_fmac_f32_e32 v19, v21, v20
	v_lshlrev_b32_e32 v21, 16, v40
	v_mul_f32_e32 v22, 0x3d372713, v21
	v_mul_f32_e32 v22, v22, v21
	v_fma_f32 v22, v22, v21, v21
	v_mul_f32_e32 v22, 0x3f4c422a, v22
	v_mul_f32_e32 v22, 0xc038aa3b, v22
	v_exp_f32_e32 v22, v22
	v_lshlrev_b32_e32 v20, 16, v90
	v_add_f32_e32 v20, v19, v20
	v_add_f32_e32 v22, 1.0, v22
	v_rcp_f32_e32 v22, v22
	s_nop 0
	v_mul_f32_e32 v21, v22, v21
	v_mul_f32_e32 v20, v21, v20
	v_bfe_u32 v21, v20, 16, 1
	v_add3_u32 v20, v20, v21, s61
	global_store_short_d16_hi v[44:45], v20, off
	v_lshlrev_b32_e32 v20, 16, v18
	v_exp_f32_e32 v20, v20
	v_lshlrev_b32_e32 v18, 16, v89
	v_fmac_f32_e32 v41, v20, v19
	v_mul_f32_e32 v19, 0x3d372713, v1
	v_mul_f32_e32 v19, v19, v1
	v_fma_f32 v19, v19, v1, v1
	v_mul_f32_e32 v19, 0x3f4c422a, v19
	v_mul_f32_e32 v19, 0xc038aa3b, v19
	v_exp_f32_e32 v19, v19
	v_add_f32_e32 v18, v41, v18
	v_add_f32_e32 v19, 1.0, v19
	v_rcp_f32_e32 v19, v19
	s_nop 0
	v_mul_f32_e32 v1, v19, v1
	v_mul_f32_e32 v1, v1, v18
	v_bfe_u32 v18, v1, 16, 1
	v_add3_u32 v1, v1, v18, s61
	global_store_short_d16_hi v[42:43], v1, off
	s_cbranch_scc1 .LBB0_114
	s_waitcnt vmcnt(16)
	v_mov_b64_e32 v[32:33], v[16:17]
	v_mov_b32_e32 v1, v68
	v_mov_b32_e32 v40, v69
	v_mov_b32_e32 v84, v70
	v_mov_b32_e32 v85, v71
	v_mov_b32_e32 v86, v72
	v_mov_b32_e32 v87, v73
	v_mov_b32_e32 v88, v74
	v_mov_b32_e32 v91, v75
	v_mov_b32_e32 v93, v76
	v_mov_b32_e32 v95, v77
	v_mov_b32_e32 v98, v78
	v_mov_b32_e32 v100, v79
	v_mov_b32_e32 v102, v80
	v_mov_b32_e32 v104, v81
	v_mov_b32_e32 v106, v82
	v_mov_b32_e32 v109, v83
	v_mov_b64_e32 v[30:31], v[14:15]
	v_mov_b64_e32 v[28:29], v[12:13]
	v_mov_b64_e32 v[26:27], v[10:11]
	v_mov_b64_e32 v[24:25], v[8:9]
	v_mov_b64_e32 v[22:23], v[6:7]
	v_mov_b64_e32 v[20:21], v[4:5]
	v_mov_b64_e32 v[18:19], v[2:3]
	s_branch .LBB0_126
.Lsf_b_last:
	s_waitcnt vmcnt(0)
	s_branch .Lsf_b_go

; #define GAS __attribute__((address_space(1)))
; __device__ __forceinline__ void kvpost_phase(const GAS bf16_t* __restrict__ KVR, const GAS float* __restrict__ sskv, GAS bf16_t* __restrict__ Kb, GAS bf16_t* __restrict__ Vt, int gtid, int NT) {
;     ...
;     for (int task = gtid; task < MALL * 64; task += NT) {
;         const int row = task >> 6, c = task & 63, h = c >> 3, dd = (c & 7) * 8; const bool lat = row < MLAT;
;         const int b = lat ? (row >> 13) : ((row - MLAT) >> 8), pos = lat ? (CTX + (row & 8191)) : ((row - MLAT) & 255);
;         const float rs = rsqrtf(sskv[row] * (1.f / 128.f) + EPS);
;         const u32x4 mine = __builtin_nontemporal_load((const GAS u32x4*)(KVR + (size_t)row * 1024 + h * 128 + dd));
.LBB0_173:
	v_bfe_u32 v10, v9, 3, 3
	v_and_b32_e32 v11, 56, v8
	v_lshlrev_b32_e32 v6, 8, v10
	v_mov_b32_e32 v7, v0
	v_lshlrev_b32_e32 v2, 1, v11
	v_mov_b32_e32 v3, v0
	s_mov_b32 s2, 0x41ffff
	v_add_u32_e32 v8, s1, v8
	v_mov_b64_e32 v[4:5], s[84:85]
	v_mov_b32_e32 v20, v9
	v_add_u32_e32 v21, s3, v20
	v_add_u32_e32 v22, s3, v21
	v_add_u32_e32 v23, s3, v22
	v_ashrrev_i32_e32 v24, 6, v20
	v_ashrrev_i32_e32 v25, 31, v24
	v_lshl_add_u64 v[32:33], v[24:25], 2, s[86:87]
	global_load_dword v40, v[32:33], off
	v_lshlrev_b64 v[34:35], 11, v[24:25]
	v_lshl_add_u64 v[34:35], s[38:39], 0, v[34:35]
	v_lshl_add_u64 v[34:35], v[34:35], 0, v[6:7]
	v_lshl_add_u64 v[34:35], v[34:35], 0, v[2:3]
	global_load_dwordx4 v[44:47], v[34:35], off nt
	v_ashrrev_i32_e32 v26, 6, v21
	v_ashrrev_i32_e32 v27, 31, v26
	v_lshl_add_u64 v[32:33], v[26:27], 2, s[86:87]
	global_load_dword v41, v[32:33], off
	v_lshlrev_b64 v[34:35], 11, v[26:27]
	v_lshl_add_u64 v[34:35], s[38:39], 0, v[34:35]
	v_lshl_add_u64 v[34:35], v[34:35], 0, v[6:7]
	v_lshl_add_u64 v[34:35], v[34:35], 0, v[2:3]
	global_load_dwordx4 v[48:51], v[34:35], off nt
	v_ashrrev_i32_e32 v28, 6, v22
	v_ashrrev_i32_e32 v29, 31, v28
	v_lshl_add_u64 v[32:33], v[28:29], 2, s[86:87]
	global_load_dword v42, v[32:33], off
	v_lshlrev_b64 v[34:35], 11, v[28:29]
	v_lshl_add_u64 v[34:35], s[38:39], 0, v[34:35]
	v_lshl_add_u64 v[34:35], v[34:35], 0, v[6:7]
	v_lshl_add_u64 v[34:35], v[34:35], 0, v[2:3]
	global_load_dwordx4 v[52:55], v[34:35], off nt
	v_ashrrev_i32_e32 v30, 6, v23
	v_ashrrev_i32_e32 v31, 31, v30
	v_lshl_add_u64 v[32:33], v[30:31], 2, s[86:87]
	global_load_dword v43, v[32:33], off
	v_lshlrev_b64 v[34:35], 11, v[30:31]
	v_lshl_add_u64 v[34:35], s[38:39], 0, v[34:35]
	v_lshl_add_u64 v[34:35], v[34:35], 0, v[6:7]
	v_lshl_add_u64 v[34:35], v[34:35], 0, v[2:3]
	global_load_dwordx4 v[56:59], v[34:35], off nt
	s_waitcnt vmcnt(0)
; #define GAS __attribute__((address_space(1)))
; __device__ __forceinline__ unsigned pk2(float lo, float hi) { return cvtpk(lo, hi); }
; __device__ __forceinline__ float bflo(unsigned w) { return __uint_as_float(w << 16); }
; __device__ __forceinline__ float bfhi(unsigned w) { return __uint_as_float(w & 0xffff0000u); }
; __device__ __forceinline__ void kvpost_phase(const GAS bf16_t* __restrict__ KVR, const GAS float* __restrict__ sskv, GAS bf16_t* __restrict__ Kb, GAS bf16_t* __restrict__ Vt, int gtid, int NT) {
;     ...
;         const int row = task >> 6, c = task & 63, h = c >> 3, dd = (c & 7) * 8; const bool lat = row < MLAT;
;         const int b = lat ? (row >> 13) : ((row - MLAT) >> 8), pos = lat ? (CTX + (row & 8191)) : ((row - MLAT) & 255);
;         const float rs = rsqrtf(sskv[row] * (1.f / 128.f) + EPS);
;         const u32x4 mine = __builtin_nontemporal_load((const GAS u32x4*)(KVR + (size_t)row * 1024 + h * 128 + dd));
;         u32x4 w;
; #pragma unroll
;         for (int j = 0; j < 4; ++j) w[j] = pk2(bflo(mine[j]) * rs, bfhi(mine[j]) * rs);
;         *(GAS u32x4*)(Kb + ((size_t)(b * 8 + h) * KVLEN + pos) * 96 + dd) = w;
	v_fmamk_f32 v34, v40, 0x3c000000, v146
	v_cmp_gt_f32_e64 s[6:7], s14, v34
	v_mul_f32_e32 v35, 0x4b800000, v34
	s_nop 0
	v_cndmask_b32_e64 v34, v34, v35, s[6:7]
	v_rsq_f32_e32 v34, v34
	s_nop 0
	v_mul_f32_e32 v35, 0x45800000, v34
	v_cndmask_b32_e64 v36, v34, v35, s[6:7]
	v_lshlrev_b32_e32 v38, 16, v44
	v_and_b32_e32 v39, 0xffff0000, v44
	v_pk_mul_f32 v[38:39], v[36:37], v[38:39] op_sel_hi:[0,1]
	v_cvt_pk_bf16_f32 v44, v38, v39
	v_lshlrev_b32_e32 v38, 16, v45
	v_and_b32_e32 v39, 0xffff0000, v45
	v_pk_mul_f32 v[38:39], v[36:37], v[38:39] op_sel_hi:[0,1]
	v_cvt_pk_bf16_f32 v45, v38, v39
	v_lshlrev_b32_e32 v38, 16, v46
	v_and_b32_e32 v39, 0xffff0000, v46
	v_pk_mul_f32 v[38:39], v[36:37], v[38:39] op_sel_hi:[0,1]
	v_cvt_pk_bf16_f32 v46, v38, v39
	v_lshlrev_b32_e32 v38, 16, v47
	v_and_b32_e32 v39, 0xffff0000, v47
	v_pk_mul_f32 v[38:39], v[36:37], v[38:39] op_sel_hi:[0,1]
	v_cvt_pk_bf16_f32 v47, v38, v39
	v_cmp_gt_i32_e32 vcc, s69, v24
	v_ashrrev_i32_e32 v34, 19, v20
	v_add_u32_e32 v35, 0xffff0000, v24
	v_lshrrev_b32_e32 v35, 8, v35
	v_and_b32_e32 v37, 0x1fff, v24
	v_cndmask_b32_e32 v34, v35, v34, vcc
	v_add_u32_e32 v37, 0x100, v37
	v_and_b32_e32 v35, 0xff, v24
	v_cndmask_b32_e32 v16, v35, v37, vcc
	v_lshl_or_b32 v34, v34, 3, v10
	v_mov_b32_e32 v17, v0
	v_mad_i64_i32 v[16:17], s[6:7], v34, s4, v[16:17]
	v_mad_u64_u32 v[60:61], s[6:7], v16, s63, v[4:5]
	v_mad_i32_i24 v61, v17, s63, v61
	v_lshl_add_u64 v[16:17], v[60:61], 0, v[2:3]
	global_store_dwordx4 v[16:17], v[44:47], off
	v_fmamk_f32 v34, v41, 0x3c000000, v146
	v_cmp_gt_f32_e64 s[6:7], s14, v34
	v_mul_f32_e32 v35, 0x4b800000, v34
	s_nop 0
	v_cndmask_b32_e64 v34, v34, v35, s[6:7]
	v_rsq_f32_e32 v34, v34
	s_nop 0
	v_mul_f32_e32 v35, 0x45800000, v34
	v_cndmask_b32_e64 v36, v34, v35, s[6:7]
	v_lshlrev_b32_e32 v38, 16, v48
	v_and_b32_e32 v39, 0xffff0000, v48
	v_pk_mul_f32 v[38:39], v[36:37], v[38:39] op_sel_hi:[0,1]
	v_cvt_pk_bf16_f32 v48, v38, v39
	v_lshlrev_b32_e32 v38, 16, v49
	v_and_b32_e32 v39, 0xffff0000, v49
	v_pk_mul_f32 v[38:39], v[36:37], v[38:39] op_sel_hi:[0,1]
	v_cvt_pk_bf16_f32 v49, v38, v39
	v_lshlrev_b32_e32 v38, 16, v50
	v_and_b32_e32 v39, 0xffff0000, v50
	v_pk_mul_f32 v[38:39], v[36:37], v[38:39] op_sel_hi:[0,1]
	v_cvt_pk_bf16_f32 v50, v38, v39
	v_lshlrev_b32_e32 v38, 16, v51
	v_and_b32_e32 v39, 0xffff0000, v51
	v_pk_mul_f32 v[38:39], v[36:37], v[38:39] op_sel_hi:[0,1]
	v_cvt_pk_bf16_f32 v51, v38, v39
	v_cmp_gt_i32_e32 vcc, s69, v26
	v_ashrrev_i32_e32 v34, 19, v21
	v_add_u32_e32 v35, 0xffff0000, v26
	v_lshrrev_b32_e32 v35, 8, v35
	v_and_b32_e32 v37, 0x1fff, v26
	v_cndmask_b32_e32 v34, v35, v34, vcc
	v_add_u32_e32 v37, 0x100, v37
	v_and_b32_e32 v35, 0xff, v26
	v_cndmask_b32_e32 v16, v35, v37, vcc
	v_lshl_or_b32 v34, v34, 3, v10
	v_mov_b32_e32 v17, v0
	v_mad_i64_i32 v[16:17], s[6:7], v34, s4, v[16:17]
	v_mad_u64_u32 v[60:61], s[6:7], v16, s63, v[4:5]
	v_mad_i32_i24 v61, v17, s63, v61
	v_lshl_add_u64 v[16:17], v[60:61], 0, v[2:3]
	global_store_dwordx4 v[16:17], v[48:51], off
	v_fmamk_f32 v34, v42, 0x3c000000, v146
	v_cmp_gt_f32_e64 s[6:7], s14, v34
	v_mul_f32_e32 v35, 0x4b800000, v34
	s_nop 0
	v_cndmask_b32_e64 v34, v34, v35, s[6:7]
	v_rsq_f32_e32 v34, v34
	s_nop 0
	v_mul_f32_e32 v35, 0x45800000, v34
	v_cndmask_b32_e64 v36, v34, v35, s[6:7]
	v_lshlrev_b32_e32 v38, 16, v52
	v_and_b32_e32 v39, 0xffff0000, v52
	v_pk_mul_f32 v[38:39], v[36:37], v[38:39] op_sel_hi:[0,1]
	v_cvt_pk_bf16_f32 v52, v38, v39
	v_lshlrev_b32_e32 v38, 16, v53
	v_and_b32_e32 v39, 0xffff0000, v53
	v_pk_mul_f32 v[38:39], v[36:37], v[38:39] op_sel_hi:[0,1]
	v_cvt_pk_bf16_f32 v53, v38, v39
	v_lshlrev_b32_e32 v38, 16, v54
	v_and_b32_e32 v39, 0xffff0000, v54
	v_pk_mul_f32 v[38:39], v[36:37], v[38:39] op_sel_hi:[0,1]
	v_cvt_pk_bf16_f32 v54, v38, v39
	v_lshlrev_b32_e32 v38, 16, v55
	v_and_b32_e32 v39, 0xffff0000, v55
	v_pk_mul_f32 v[38:39], v[36:37], v[38:39] op_sel_hi:[0,1]
	v_cvt_pk_bf16_f32 v55, v38, v39
	v_cmp_gt_i32_e32 vcc, s69, v28
	v_ashrrev_i32_e32 v34, 19, v22
	v_add_u32_e32 v35, 0xffff0000, v28
	v_lshrrev_b32_e32 v35, 8, v35
	v_and_b32_e32 v37, 0x1fff, v28
	v_cndmask_b32_e32 v34, v35, v34, vcc
	v_add_u32_e32 v37, 0x100, v37
	v_and_b32_e32 v35, 0xff, v28
	v_cndmask_b32_e32 v16, v35, v37, vcc
	v_lshl_or_b32 v34, v34, 3, v10
	v_mov_b32_e32 v17, v0
	v_mad_i64_i32 v[16:17], s[6:7], v34, s4, v[16:17]
	v_mad_u64_u32 v[60:61], s[6:7], v16, s63, v[4:5]
	v_mad_i32_i24 v61, v17, s63, v61
	v_lshl_add_u64 v[16:17], v[60:61], 0, v[2:3]
	global_store_dwordx4 v[16:17], v[52:55], off
	v_fmamk_f32 v34, v43, 0x3c000000, v146
	v_cmp_gt_f32_e64 s[6:7], s14, v34
	v_mul_f32_e32 v35, 0x4b800000, v34
	s_nop 0
	v_cndmask_b32_e64 v34, v34, v35, s[6:7]
	v_rsq_f32_e32 v34, v34
	s_nop 0
	v_mul_f32_e32 v35, 0x45800000, v34
	v_cndmask_b32_e64 v36, v34, v35, s[6:7]
	v_lshlrev_b32_e32 v38, 16, v56
	v_and_b32_e32 v39, 0xffff0000, v56
	v_pk_mul_f32 v[38:39], v[36:37], v[38:39] op_sel_hi:[0,1]
	v_cvt_pk_bf16_f32 v56, v38, v39
	v_lshlrev_b32_e32 v38, 16, v57
	v_and_b32_e32 v39, 0xffff0000, v57
	v_pk_mul_f32 v[38:39], v[36:37], v[38:39] op_sel_hi:[0,1]
	v_cvt_pk_bf16_f32 v57, v38, v39
	v_lshlrev_b32_e32 v38, 16, v58
	v_and_b32_e32 v39, 0xffff0000, v58
	v_pk_mul_f32 v[38:39], v[36:37], v[38:39] op_sel_hi:[0,1]
	v_cvt_pk_bf16_f32 v58, v38, v39
	v_lshlrev_b32_e32 v38, 16, v59
	v_and_b32_e32 v39, 0xffff0000, v59
	v_pk_mul_f32 v[38:39], v[36:37], v[38:39] op_sel_hi:[0,1]
	v_cvt_pk_bf16_f32 v59, v38, v39
	v_cmp_gt_i32_e32 vcc, s69, v30
	v_ashrrev_i32_e32 v34, 19, v23
	v_add_u32_e32 v35, 0xffff0000, v30
	v_lshrrev_b32_e32 v35, 8, v35
	v_and_b32_e32 v37, 0x1fff, v30
	v_cndmask_b32_e32 v34, v35, v34, vcc
	v_add_u32_e32 v37, 0x100, v37
	v_and_b32_e32 v35, 0xff, v30
	v_cndmask_b32_e32 v16, v35, v37, vcc
	v_lshl_or_b32 v34, v34, 3, v10
	v_mov_b32_e32 v17, v0
	v_mad_i64_i32 v[16:17], s[6:7], v34, s4, v[16:17]
	v_mad_u64_u32 v[60:61], s[6:7], v16, s63, v[4:5]
	v_mad_i32_i24 v61, v17, s63, v61
	v_lshl_add_u64 v[16:17], v[60:61], 0, v[2:3]
	global_store_dwordx4 v[16:17], v[56:59], off
	v_add_u32_e32 v9, s3, v23
	v_cmp_lt_i32_e32 vcc, s2, v9
	s_or_b64 s[10:11], vcc, s[10:11]
	s_andn2_b64 exec, exec, s[10:11]
	s_cbranch_execnz .LBB0_173

; #define GAS __attribute__((address_space(1)))
; __device__ __forceinline__ float bflo(unsigned w) { return __uint_as_float(w << 16); }
; __device__ __forceinline__ float bfhi(unsigned w) { return __uint_as_float(w & 0xffff0000u); }
; __device__ __forceinline__ void ss_phase(const GAS bf16_t* __restrict__ P, GAS float* __restrict__ ssq, GAS float* __restrict__ sskv, int gw, int NGW, int lane) {
; #pragma unroll 4
;     for (int m = gw; m < MALL; m += NGW) {
;         const u32x2 q = *(const GAS u32x2*)(P + (size_t)m * PW + 1024 + 4 * lane); const unsigned k = *(const GAS unsigned*)(P + (size_t)m * PW + 1280 + 2 * lane);
;         float a = bflo(q.x) * bflo(q.x) + bfhi(q.x) * bfhi(q.x) + bflo(q.y) * bflo(q.y) + bfhi(q.y) * bfhi(q.y), c = bflo(k) * bflo(k) + bfhi(k) * bfhi(k);
;         a = wave_sum(a); c = wave_sum(c);
;         if (lane == 0) { ssq[m] = a; sskv[m] = c; }
;     }
; }
.Lss_pre:
	s_mul_i32 s20, s18, 0xc00
	s_mul_hi_i32 s21, s18, 0xc00
.Lss_4:
	s_mul_i32 s2, s18, 3
	s_add_i32 s2, s2, s1
	s_cmp_gt_i32 s2, 0x107ff
	s_cbranch_scc1 .Lss_tail
	s_add_u32 s24, s10, s20
	s_addc_u32 s25, s11, s21
	s_add_u32 s26, s24, s20
	s_addc_u32 s27, s25, s21
	s_add_u32 s40, s26, s20
	s_addc_u32 s41, s27, s21
	v_lshl_add_u64 v[16:17], s[10:11], 0, v[4:5]
	v_lshl_add_u64 v[18:19], s[24:25], 0, v[4:5]
	v_lshl_add_u64 v[20:21], s[26:27], 0, v[4:5]
	v_lshl_add_u64 v[22:23], s[40:41], 0, v[4:5]
	global_load_dwordx2 v[24:25], v[16:17], off
	global_load_dwordx2 v[26:27], v[18:19], off
	global_load_dwordx2 v[28:29], v[20:21], off
	global_load_dwordx2 v[30:31], v[22:23], off
	v_lshl_add_u64 v[16:17], s[10:11], 0, v[2:3]
	v_lshl_add_u64 v[18:19], s[24:25], 0, v[2:3]
	v_lshl_add_u64 v[20:21], s[26:27], 0, v[2:3]
	v_lshl_add_u64 v[22:23], s[40:41], 0, v[2:3]
	global_load_dword v32, v[16:17], off
	global_load_dword v33, v[18:19], off
	global_load_dword v34, v[20:21], off
	global_load_dword v35, v[22:23], off
	s_waitcnt vmcnt(0)
	v_lshlrev_b32_e32 v44, 16, v24
	v_and_b32_e32 v36, 0xffff0000, v24
	v_mul_f32_e32 v36, v36, v36
	v_fmac_f32_e32 v36, v44, v44
	v_lshlrev_b32_e32 v44, 16, v25
	v_fmac_f32_e32 v36, v44, v44
	v_and_b32_e32 v44, 0xffff0000, v25
	v_fmac_f32_e32 v36, v44, v44
	v_lshlrev_b32_e32 v44, 16, v32
	v_and_b32_e32 v40, 0xffff0000, v32
	v_mul_f32_e32 v40, v40, v40
	v_fmac_f32_e32 v40, v44, v44
	v_lshlrev_b32_e32 v44, 16, v26
	v_and_b32_e32 v37, 0xffff0000, v26
	v_mul_f32_e32 v37, v37, v37
	v_fmac_f32_e32 v37, v44, v44
	v_lshlrev_b32_e32 v44, 16, v27
	v_fmac_f32_e32 v37, v44, v44
	v_and_b32_e32 v44, 0xffff0000, v27
	v_fmac_f32_e32 v37, v44, v44
	v_lshlrev_b32_e32 v44, 16, v33
	v_and_b32_e32 v41, 0xffff0000, v33
	v_mul_f32_e32 v41, v41, v41
	v_fmac_f32_e32 v41, v44, v44
	v_lshlrev_b32_e32 v44, 16, v28
	v_and_b32_e32 v38, 0xffff0000, v28
	v_mul_f32_e32 v38, v38, v38
	v_fmac_f32_e32 v38, v44, v44
	v_lshlrev_b32_e32 v44, 16, v29
	v_fmac_f32_e32 v38, v44, v44
	v_and_b32_e32 v44, 0xffff0000, v29
	v_fmac_f32_e32 v38, v44, v44
	v_lshlrev_b32_e32 v44, 16, v34
	v_and_b32_e32 v42, 0xffff0000, v34
	v_mul_f32_e32 v42, v42, v42
	v_fmac_f32_e32 v42, v44, v44
	v_lshlrev_b32_e32 v44, 16, v30
	v_and_b32_e32 v39, 0xffff0000, v30
	v_mul_f32_e32 v39, v39, v39
	v_fmac_f32_e32 v39, v44, v44
	v_lshlrev_b32_e32 v44, 16, v31
	v_fmac_f32_e32 v39, v44, v44
	v_and_b32_e32 v44, 0xffff0000, v31
	v_fmac_f32_e32 v39, v44, v44
	v_lshlrev_b32_e32 v44, 16, v35
	v_and_b32_e32 v43, 0xffff0000, v35
	v_mul_f32_e32 v43, v43, v43
	v_fmac_f32_e32 v43, v44, v44
	ds_bpermute_b32 v48, v1, v36
	ds_bpermute_b32 v52, v1, v40
	ds_bpermute_b32 v49, v1, v37
	ds_bpermute_b32 v53, v1, v41
	ds_bpermute_b32 v50, v1, v38
	ds_bpermute_b32 v54, v1, v42
	ds_bpermute_b32 v51, v1, v39
	ds_bpermute_b32 v55, v1, v43
	s_waitcnt lgkmcnt(0)
	v_add_f32_e32 v36, v36, v48
	v_add_f32_e32 v40, v40, v52
	v_add_f32_e32 v37, v37, v49
	v_add_f32_e32 v41, v41, v53
	v_add_f32_e32 v38, v38, v50
	v_add_f32_e32 v42, v42, v54
	v_add_f32_e32 v39, v39, v51
	v_add_f32_e32 v43, v43, v55
	ds_bpermute_b32 v48, v6, v36
	ds_bpermute_b32 v52, v6, v40
	ds_bpermute_b32 v49, v6, v37
	ds_bpermute_b32 v53, v6, v41
	ds_bpermute_b32 v50, v6, v38
	ds_bpermute_b32 v54, v6, v42
	ds_bpermute_b32 v51, v6, v39
	ds_bpermute_b32 v55, v6, v43
	s_waitcnt lgkmcnt(0)
	v_add_f32_e32 v36, v36, v48
	v_add_f32_e32 v40, v40, v52
	v_add_f32_e32 v37, v37, v49
	v_add_f32_e32 v41, v41, v53
	v_add_f32_e32 v38, v38, v50
	v_add_f32_e32 v42, v42, v54
	v_add_f32_e32 v39, v39, v51
	v_add_f32_e32 v43, v43, v55
	ds_bpermute_b32 v48, v7, v36
	ds_bpermute_b32 v52, v7, v40
	ds_bpermute_b32 v49, v7, v37
	ds_bpermute_b32 v53, v7, v41
	ds_bpermute_b32 v50, v7, v38
	ds_bpermute_b32 v54, v7, v42
	ds_bpermute_b32 v51, v7, v39
	ds_bpermute_b32 v55, v7, v43
	s_waitcnt lgkmcnt(0)
	v_add_f32_e32 v36, v36, v48
	v_add_f32_e32 v40, v40, v52
	v_add_f32_e32 v37, v37, v49
	v_add_f32_e32 v41, v41, v53
	v_add_f32_e32 v38, v38, v50
	v_add_f32_e32 v42, v42, v54
	v_add_f32_e32 v39, v39, v51
	v_add_f32_e32 v43, v43, v55
	ds_bpermute_b32 v48, v8, v36
	ds_bpermute_b32 v52, v8, v40
	ds_bpermute_b32 v49, v8, v37
	ds_bpermute_b32 v53, v8, v41
	ds_bpermute_b32 v50, v8, v38
	ds_bpermute_b32 v54, v8, v42
	ds_bpermute_b32 v51, v8, v39
	ds_bpermute_b32 v55, v8, v43
	s_waitcnt lgkmcnt(0)
	v_add_f32_e32 v36, v36, v48
	v_add_f32_e32 v40, v40, v52
	v_add_f32_e32 v37, v37, v49
	v_add_f32_e32 v41, v41, v53
	v_add_f32_e32 v38, v38, v50
	v_add_f32_e32 v42, v42, v54
	v_add_f32_e32 v39, v39, v51
	v_add_f32_e32 v43, v43, v55
	ds_bpermute_b32 v48, v9, v36
	ds_bpermute_b32 v52, v9, v40
	ds_bpermute_b32 v49, v9, v37
	ds_bpermute_b32 v53, v9, v41
	ds_bpermute_b32 v50, v9, v38
	ds_bpermute_b32 v54, v9, v42
	ds_bpermute_b32 v51, v9, v39
	ds_bpermute_b32 v55, v9, v43
	s_waitcnt lgkmcnt(0)
	v_add_f32_e32 v36, v36, v48
	v_add_f32_e32 v40, v40, v52
	v_add_f32_e32 v37, v37, v49
	v_add_f32_e32 v41, v41, v53
	v_add_f32_e32 v38, v38, v50
	v_add_f32_e32 v42, v42, v54
	v_add_f32_e32 v39, v39, v51
	v_add_f32_e32 v43, v43, v55
	ds_bpermute_b32 v48, v10, v36
	ds_bpermute_b32 v52, v10, v40
	ds_bpermute_b32 v49, v10, v37
	ds_bpermute_b32 v53, v10, v41
	ds_bpermute_b32 v50, v10, v38
	ds_bpermute_b32 v54, v10, v42
	ds_bpermute_b32 v51, v10, v39
	ds_bpermute_b32 v55, v10, v43
	s_waitcnt lgkmcnt(0)
	v_add_f32_e32 v36, v36, v48
	v_add_f32_e32 v40, v40, v52
	v_add_f32_e32 v37, v37, v49
	v_add_f32_e32 v41, v41, v53
	v_add_f32_e32 v38, v38, v50
	v_add_f32_e32 v42, v42, v54
	v_add_f32_e32 v39, v39, v51
	v_add_f32_e32 v43, v43, v55
	s_and_saveexec_b64 s[56:57], vcc
	v_mov_b32_e32 v45, 0x80000
	s_add_u32 s24, s6, s8
	s_addc_u32 s25, s7, s9
	s_add_u32 s26, s24, s8
	s_addc_u32 s27, s25, s9
	s_add_u32 s40, s26, s8
	s_addc_u32 s41, s27, s9
	global_store_dword v0, v36, s[6:7]
	global_store_dword v45, v40, s[6:7]
	global_store_dword v0, v37, s[24:25]
	global_store_dword v45, v41, s[24:25]
	global_store_dword v0, v38, s[26:27]
	global_store_dword v45, v42, s[26:27]
	global_store_dword v0, v39, s[40:41]
	global_store_dword v45, v43, s[40:41]
	s_or_b64 exec, exec, s[56:57]
	s_lshl_b32 s2, s18, 2
	s_add_i32 s1, s1, s2
	s_add_u32 s6, s40, s8
	s_addc_u32 s7, s41, s9
	s_lshl_b64 s[22:23], s[20:21], 2
	s_add_u32 s10, s10, s22
	s_addc_u32 s11, s11, s23
	s_branch .Lss_4
.Lss_tail:
	s_cmp_gt_i32 s1, 0x107ff
	s_cbranch_scc1 .LBB0_233
